# S5 cross-chunk scan (phase 5): both scan loops rewritten as straight-line code with 12 chunks of loads in flight, same arithmetic (on v12)
# baseline (speedup 1.0000x reference)
; __global__ void __launch_bounds__(512, 2) fwd_megakernel(Params Pk) {
;     ...
;         for (int task = bx; task < NG * 4; task += G) {
;             const int g = task >> 2, dir = (task >> 1) & 1, kind = task & 1;
;             const f32x2 a = aL[(g * 2 + dir) * 64 + lane];
;             const float* E = Send + (size_t)g * NCH * 256 + dir * 128 + lane; bf16_t* S = Sin + (size_t)g * NCH * 256 + dir * 128 + lane;
;             const int cfirst = kind ? (dir ? 256 + 32 * wid + 31 : 256 + 32 * wid) : (dir ? 255 - 32 * wid : 32 * wid), cstep = dir ? -1 : 1;
;             float sr = 0.f, si = 0.f;
;             if (kind == 0) {
; #pragma unroll 8
;                 for (int i = 0; i < 32; ++i) { const size_t o = (size_t)(cfirst + cstep * i) * 256;
;                     const float er = E[o] + E[o + HALF2], ei = E[o + 64] + E[o + 64 + HALF2];
;                     const float nr = a.x * sr - a.y * si + er, ni = a.x * si + a.y * sr + ei; sr = nr; si = ni; }
;                 endst[wid * 64 + lane] = (f32x2){sr, si};
.LBB0_676:
	v_readfirstlane_b32 s44, v20
	v_readfirstlane_b32 s45, v21
	s_lshl_b32 s48, s35, 10
	s_ashr_i32 s49, s48, 31
	v_mov_b32_e32 v22, 0
	v_mov_b32_e32 v23, 0
	s_nop 4
	s_add_u32 s54, s44, s31
	s_addc_u32 s55, s45, 0
	global_load_dword v104, v10, s[44:45]
	global_load_dword v105, v10, s[44:45] offset:256
	global_load_dword v106, v10, s[54:55]
	global_load_dword v107, v10, s[54:55] offset:256
	s_add_u32 s46, s44, s48
	s_addc_u32 s47, s45, s49
	s_add_u32 s56, s54, s48
	s_addc_u32 s57, s55, s49
	global_load_dword v108, v10, s[46:47]
	global_load_dword v109, v10, s[46:47] offset:256
	global_load_dword v110, v10, s[56:57]
	global_load_dword v111, v10, s[56:57] offset:256
	s_add_u32 s50, s46, s48
	s_addc_u32 s51, s47, s49
	s_add_u32 s58, s56, s48
	s_addc_u32 s59, s57, s49
	global_load_dword v112, v10, s[50:51]
	global_load_dword v113, v10, s[50:51] offset:256
	global_load_dword v114, v10, s[58:59]
	global_load_dword v115, v10, s[58:59] offset:256
	s_add_u32 s52, s50, s48
	s_addc_u32 s53, s51, s49
	s_add_u32 s60, s58, s48
	s_addc_u32 s61, s59, s49
	global_load_dword v116, v10, s[52:53]
	global_load_dword v117, v10, s[52:53] offset:256
	global_load_dword v118, v10, s[60:61]
	global_load_dword v119, v10, s[60:61] offset:256
	s_add_u32 s44, s52, s48
	s_addc_u32 s45, s53, s49
	s_add_u32 s54, s60, s48
	s_addc_u32 s55, s61, s49
	global_load_dword v120, v10, s[44:45]
	global_load_dword v121, v10, s[44:45] offset:256
	global_load_dword v122, v10, s[54:55]
	global_load_dword v123, v10, s[54:55] offset:256
	s_add_u32 s46, s44, s48
	s_addc_u32 s47, s45, s49
	s_add_u32 s56, s54, s48
	s_addc_u32 s57, s55, s49
	global_load_dword v124, v10, s[46:47]
	global_load_dword v125, v10, s[46:47] offset:256
	global_load_dword v126, v10, s[56:57]
	global_load_dword v127, v10, s[56:57] offset:256
	s_add_u32 s50, s46, s48
	s_addc_u32 s51, s47, s49
	s_add_u32 s58, s56, s48
	s_addc_u32 s59, s57, s49
	global_load_dword v128, v10, s[50:51]
	global_load_dword v129, v10, s[50:51] offset:256
	global_load_dword v130, v10, s[58:59]
	global_load_dword v131, v10, s[58:59] offset:256
	s_add_u32 s52, s50, s48
	s_addc_u32 s53, s51, s49
	s_add_u32 s60, s58, s48
	s_addc_u32 s61, s59, s49
	global_load_dword v132, v10, s[52:53]
	global_load_dword v133, v10, s[52:53] offset:256
	global_load_dword v134, v10, s[60:61]
	global_load_dword v135, v10, s[60:61] offset:256
	s_add_u32 s44, s52, s48
	s_addc_u32 s45, s53, s49
	s_add_u32 s54, s60, s48
	s_addc_u32 s55, s61, s49
	global_load_dword v136, v10, s[44:45]
	global_load_dword v137, v10, s[44:45] offset:256
	global_load_dword v138, v10, s[54:55]
	global_load_dword v139, v10, s[54:55] offset:256
	s_add_u32 s46, s44, s48
	s_addc_u32 s47, s45, s49
	s_add_u32 s56, s54, s48
	s_addc_u32 s57, s55, s49
	global_load_dword v140, v10, s[46:47]
	global_load_dword v141, v10, s[46:47] offset:256
	global_load_dword v142, v10, s[56:57]
	global_load_dword v143, v10, s[56:57] offset:256
	s_add_u32 s50, s46, s48
	s_addc_u32 s51, s47, s49
	s_add_u32 s58, s56, s48
	s_addc_u32 s59, s57, s49
	global_load_dword v144, v10, s[50:51]
	global_load_dword v145, v10, s[50:51] offset:256
	global_load_dword v146, v10, s[58:59]
	global_load_dword v147, v10, s[58:59] offset:256
	s_add_u32 s52, s50, s48
	s_addc_u32 s53, s51, s49
	s_add_u32 s60, s58, s48
	s_addc_u32 s61, s59, s49
	global_load_dword v148, v10, s[52:53]
	global_load_dword v149, v10, s[52:53] offset:256
	global_load_dword v150, v10, s[60:61]
	global_load_dword v151, v10, s[60:61] offset:256
	v_mul_f32_e32 v24, v13, v23
	v_mul_f32_e32 v25, v12, v23
	s_waitcnt vmcnt(44)
	v_pk_add_f32 v[26:27], v[104:105], v[106:107]
	v_fma_f32 v24, v12, v22, -v24
	v_fma_f32 v25, v13, v22, v25
	s_add_u32 s44, s52, s48
	s_addc_u32 s45, s53, s49
	s_add_u32 s54, s60, s48
	s_addc_u32 s55, s61, s49
	global_load_dword v152, v10, s[44:45]
	global_load_dword v153, v10, s[44:45] offset:256
	global_load_dword v154, v10, s[54:55]
	global_load_dword v155, v10, s[54:55] offset:256
	v_add_f32_e32 v22, v24, v26
	v_add_f32_e32 v23, v25, v27
	v_mul_f32_e32 v24, v13, v23
	v_mul_f32_e32 v25, v12, v23
	s_waitcnt vmcnt(44)
	v_pk_add_f32 v[26:27], v[108:109], v[110:111]
	v_fma_f32 v24, v12, v22, -v24
	v_fma_f32 v25, v13, v22, v25
	s_add_u32 s46, s44, s48
	s_addc_u32 s47, s45, s49
	s_add_u32 s56, s54, s48
	s_addc_u32 s57, s55, s49
	global_load_dword v156, v10, s[46:47]
	global_load_dword v157, v10, s[46:47] offset:256
	global_load_dword v158, v10, s[56:57]
	global_load_dword v159, v10, s[56:57] offset:256
	v_add_f32_e32 v22, v24, v26
	v_add_f32_e32 v23, v25, v27
	v_mul_f32_e32 v24, v13, v23
	v_mul_f32_e32 v25, v12, v23
	s_waitcnt vmcnt(44)
	v_pk_add_f32 v[26:27], v[112:113], v[114:115]
	v_fma_f32 v24, v12, v22, -v24
	v_fma_f32 v25, v13, v22, v25
	s_add_u32 s50, s46, s48
	s_addc_u32 s51, s47, s49
	s_add_u32 s58, s56, s48
	s_addc_u32 s59, s57, s49
	global_load_dword v160, v10, s[50:51]
	global_load_dword v161, v10, s[50:51] offset:256
	global_load_dword v162, v10, s[58:59]
	global_load_dword v163, v10, s[58:59] offset:256
	v_add_f32_e32 v22, v24, v26
	v_add_f32_e32 v23, v25, v27
	v_mul_f32_e32 v24, v13, v23
	v_mul_f32_e32 v25, v12, v23
	s_waitcnt vmcnt(44)
	v_pk_add_f32 v[26:27], v[116:117], v[118:119]
	v_fma_f32 v24, v12, v22, -v24
	v_fma_f32 v25, v13, v22, v25
	s_add_u32 s52, s50, s48
	s_addc_u32 s53, s51, s49
	s_add_u32 s60, s58, s48
	s_addc_u32 s61, s59, s49
	global_load_dword v164, v10, s[52:53]
	global_load_dword v165, v10, s[52:53] offset:256
	global_load_dword v166, v10, s[60:61]
	global_load_dword v167, v10, s[60:61] offset:256
	v_add_f32_e32 v22, v24, v26
	v_add_f32_e32 v23, v25, v27
	v_mul_f32_e32 v24, v13, v23
	v_mul_f32_e32 v25, v12, v23
	s_waitcnt vmcnt(44)
; __global__ void __launch_bounds__(512, 2) fwd_megakernel(Params Pk) {
;     ...
;                 for (int i = 0; i < 32; ++i) { const size_t o = (size_t)(cfirst + cstep * i) * 256;
;                     const float er = E[o] + E[o + HALF2], ei = E[o + 64] + E[o + 64 + HALF2];
;                     const float nr = a.x * sr - a.y * si + er, ni = a.x * si + a.y * sr + ei; sr = nr; si = ni; }
	v_pk_add_f32 v[26:27], v[120:121], v[122:123]
	v_fma_f32 v24, v12, v22, -v24
	v_fma_f32 v25, v13, v22, v25
	s_add_u32 s44, s52, s48
	s_addc_u32 s45, s53, s49
	s_add_u32 s54, s60, s48
	s_addc_u32 s55, s61, s49
	global_load_dword v168, v10, s[44:45]
	global_load_dword v169, v10, s[44:45] offset:256
	global_load_dword v170, v10, s[54:55]
	global_load_dword v171, v10, s[54:55] offset:256
	v_add_f32_e32 v22, v24, v26
	v_add_f32_e32 v23, v25, v27
	v_mul_f32_e32 v24, v13, v23
	v_mul_f32_e32 v25, v12, v23
	s_waitcnt vmcnt(44)
	v_pk_add_f32 v[26:27], v[124:125], v[126:127]
	v_fma_f32 v24, v12, v22, -v24
	v_fma_f32 v25, v13, v22, v25
	s_add_u32 s46, s44, s48
	s_addc_u32 s47, s45, s49
	s_add_u32 s56, s54, s48
	s_addc_u32 s57, s55, s49
	global_load_dword v172, v10, s[46:47]
	global_load_dword v173, v10, s[46:47] offset:256
	global_load_dword v174, v10, s[56:57]
	global_load_dword v175, v10, s[56:57] offset:256
	v_add_f32_e32 v22, v24, v26
	v_add_f32_e32 v23, v25, v27
	v_mul_f32_e32 v24, v13, v23
	v_mul_f32_e32 v25, v12, v23
	s_waitcnt vmcnt(44)
	v_pk_add_f32 v[26:27], v[128:129], v[130:131]
	v_fma_f32 v24, v12, v22, -v24
	v_fma_f32 v25, v13, v22, v25
	s_add_u32 s50, s46, s48
	s_addc_u32 s51, s47, s49
	s_add_u32 s58, s56, s48
	s_addc_u32 s59, s57, s49
	global_load_dword v176, v10, s[50:51]
	global_load_dword v177, v10, s[50:51] offset:256
	global_load_dword v178, v10, s[58:59]
	global_load_dword v179, v10, s[58:59] offset:256
	v_add_f32_e32 v22, v24, v26
	v_add_f32_e32 v23, v25, v27
	v_mul_f32_e32 v24, v13, v23
	v_mul_f32_e32 v25, v12, v23
	s_waitcnt vmcnt(44)
	v_pk_add_f32 v[26:27], v[132:133], v[134:135]
	v_fma_f32 v24, v12, v22, -v24
	v_fma_f32 v25, v13, v22, v25
	s_add_u32 s52, s50, s48
	s_addc_u32 s53, s51, s49
	s_add_u32 s60, s58, s48
	s_addc_u32 s61, s59, s49
	global_load_dword v180, v10, s[52:53]
	global_load_dword v181, v10, s[52:53] offset:256
	global_load_dword v182, v10, s[60:61]
	global_load_dword v183, v10, s[60:61] offset:256
	v_add_f32_e32 v22, v24, v26
	v_add_f32_e32 v23, v25, v27
	v_mul_f32_e32 v24, v13, v23
	v_mul_f32_e32 v25, v12, v23
	s_waitcnt vmcnt(44)
	v_pk_add_f32 v[26:27], v[136:137], v[138:139]
	v_fma_f32 v24, v12, v22, -v24
	v_fma_f32 v25, v13, v22, v25
	s_add_u32 s44, s52, s48
	s_addc_u32 s45, s53, s49
	s_add_u32 s54, s60, s48
	s_addc_u32 s55, s61, s49
	global_load_dword v104, v10, s[44:45]
	global_load_dword v105, v10, s[44:45] offset:256
	global_load_dword v106, v10, s[54:55]
	global_load_dword v107, v10, s[54:55] offset:256
	v_add_f32_e32 v22, v24, v26
	v_add_f32_e32 v23, v25, v27
	v_mul_f32_e32 v24, v13, v23
	v_mul_f32_e32 v25, v12, v23
	s_waitcnt vmcnt(44)
	v_pk_add_f32 v[26:27], v[140:141], v[142:143]
	v_fma_f32 v24, v12, v22, -v24
	v_fma_f32 v25, v13, v22, v25
	s_add_u32 s46, s44, s48
	s_addc_u32 s47, s45, s49
	s_add_u32 s56, s54, s48
	s_addc_u32 s57, s55, s49
	global_load_dword v108, v10, s[46:47]
	global_load_dword v109, v10, s[46:47] offset:256
	global_load_dword v110, v10, s[56:57]
	global_load_dword v111, v10, s[56:57] offset:256
	v_add_f32_e32 v22, v24, v26
	v_add_f32_e32 v23, v25, v27
	v_mul_f32_e32 v24, v13, v23
	v_mul_f32_e32 v25, v12, v23
	s_waitcnt vmcnt(44)
	v_pk_add_f32 v[26:27], v[144:145], v[146:147]
	v_fma_f32 v24, v12, v22, -v24
	v_fma_f32 v25, v13, v22, v25
	s_add_u32 s50, s46, s48
	s_addc_u32 s51, s47, s49
	s_add_u32 s58, s56, s48
	s_addc_u32 s59, s57, s49
	global_load_dword v112, v10, s[50:51]
	global_load_dword v113, v10, s[50:51] offset:256
	global_load_dword v114, v10, s[58:59]
	global_load_dword v115, v10, s[58:59] offset:256
	v_add_f32_e32 v22, v24, v26
	v_add_f32_e32 v23, v25, v27
	v_mul_f32_e32 v24, v13, v23
	v_mul_f32_e32 v25, v12, v23
	s_waitcnt vmcnt(44)
	v_pk_add_f32 v[26:27], v[148:149], v[150:151]
	v_fma_f32 v24, v12, v22, -v24
	v_fma_f32 v25, v13, v22, v25
	s_add_u32 s52, s50, s48
	s_addc_u32 s53, s51, s49
	s_add_u32 s60, s58, s48
	s_addc_u32 s61, s59, s49
	global_load_dword v116, v10, s[52:53]
	global_load_dword v117, v10, s[52:53] offset:256
	global_load_dword v118, v10, s[60:61]
	global_load_dword v119, v10, s[60:61] offset:256
	v_add_f32_e32 v22, v24, v26
	v_add_f32_e32 v23, v25, v27
	v_mul_f32_e32 v24, v13, v23
	v_mul_f32_e32 v25, v12, v23
	s_waitcnt vmcnt(44)
	v_pk_add_f32 v[26:27], v[152:153], v[154:155]
	v_fma_f32 v24, v12, v22, -v24
	v_fma_f32 v25, v13, v22, v25
	s_add_u32 s44, s52, s48
	s_addc_u32 s45, s53, s49
	s_add_u32 s54, s60, s48
	s_addc_u32 s55, s61, s49
	global_load_dword v120, v10, s[44:45]
	global_load_dword v121, v10, s[44:45] offset:256
	global_load_dword v122, v10, s[54:55]
	global_load_dword v123, v10, s[54:55] offset:256
	v_add_f32_e32 v22, v24, v26
	v_add_f32_e32 v23, v25, v27
	v_mul_f32_e32 v24, v13, v23
	v_mul_f32_e32 v25, v12, v23
	s_waitcnt vmcnt(44)
	v_pk_add_f32 v[26:27], v[156:157], v[158:159]
	v_fma_f32 v24, v12, v22, -v24
	v_fma_f32 v25, v13, v22, v25
	s_add_u32 s46, s44, s48
	s_addc_u32 s47, s45, s49
	s_add_u32 s56, s54, s48
	s_addc_u32 s57, s55, s49
	global_load_dword v124, v10, s[46:47]
	global_load_dword v125, v10, s[46:47] offset:256
	global_load_dword v126, v10, s[56:57]
	global_load_dword v127, v10, s[56:57] offset:256
	v_add_f32_e32 v22, v24, v26
	v_add_f32_e32 v23, v25, v27
	v_mul_f32_e32 v24, v13, v23
	v_mul_f32_e32 v25, v12, v23
	s_waitcnt vmcnt(44)
	v_pk_add_f32 v[26:27], v[160:161], v[162:163]
	v_fma_f32 v24, v12, v22, -v24
	v_fma_f32 v25, v13, v22, v25
	s_add_u32 s50, s46, s48
	s_addc_u32 s51, s47, s49
	s_add_u32 s58, s56, s48
	s_addc_u32 s59, s57, s49
	global_load_dword v128, v10, s[50:51]
	global_load_dword v129, v10, s[50:51] offset:256
	global_load_dword v130, v10, s[58:59]
	global_load_dword v131, v10, s[58:59] offset:256
	v_add_f32_e32 v22, v24, v26
	v_add_f32_e32 v23, v25, v27
	v_mul_f32_e32 v24, v13, v23
	v_mul_f32_e32 v25, v12, v23
	s_waitcnt vmcnt(44)
; __global__ void __launch_bounds__(512, 2) fwd_megakernel(Params Pk) {
;     ...
;             if (kind == 0) {
; #pragma unroll 8
;                 for (int i = 0; i < 32; ++i) { const size_t o = (size_t)(cfirst + cstep * i) * 256;
;                     const float er = E[o] + E[o + HALF2], ei = E[o + 64] + E[o + 64 + HALF2];
;                     const float nr = a.x * sr - a.y * si + er, ni = a.x * si + a.y * sr + ei; sr = nr; si = ni; }
;                 endst[wid * 64 + lane] = (f32x2){sr, si};
	v_pk_add_f32 v[26:27], v[164:165], v[166:167]
	v_fma_f32 v24, v12, v22, -v24
	v_fma_f32 v25, v13, v22, v25
	s_add_u32 s52, s50, s48
	s_addc_u32 s53, s51, s49
	s_add_u32 s60, s58, s48
	s_addc_u32 s61, s59, s49
	global_load_dword v132, v10, s[52:53]
	global_load_dword v133, v10, s[52:53] offset:256
	global_load_dword v134, v10, s[60:61]
	global_load_dword v135, v10, s[60:61] offset:256
	v_add_f32_e32 v22, v24, v26
	v_add_f32_e32 v23, v25, v27
	v_mul_f32_e32 v24, v13, v23
	v_mul_f32_e32 v25, v12, v23
	s_waitcnt vmcnt(44)
	v_pk_add_f32 v[26:27], v[168:169], v[170:171]
	v_fma_f32 v24, v12, v22, -v24
	v_fma_f32 v25, v13, v22, v25
	s_add_u32 s44, s52, s48
	s_addc_u32 s45, s53, s49
	s_add_u32 s54, s60, s48
	s_addc_u32 s55, s61, s49
	global_load_dword v136, v10, s[44:45]
	global_load_dword v137, v10, s[44:45] offset:256
	global_load_dword v138, v10, s[54:55]
	global_load_dword v139, v10, s[54:55] offset:256
	v_add_f32_e32 v22, v24, v26
	v_add_f32_e32 v23, v25, v27
	v_mul_f32_e32 v24, v13, v23
	v_mul_f32_e32 v25, v12, v23
	s_waitcnt vmcnt(44)
	v_pk_add_f32 v[26:27], v[172:173], v[174:175]
	v_fma_f32 v24, v12, v22, -v24
	v_fma_f32 v25, v13, v22, v25
	s_add_u32 s46, s44, s48
	s_addc_u32 s47, s45, s49
	s_add_u32 s56, s54, s48
	s_addc_u32 s57, s55, s49
	global_load_dword v140, v10, s[46:47]
	global_load_dword v141, v10, s[46:47] offset:256
	global_load_dword v142, v10, s[56:57]
	global_load_dword v143, v10, s[56:57] offset:256
	v_add_f32_e32 v22, v24, v26
	v_add_f32_e32 v23, v25, v27
	v_mul_f32_e32 v24, v13, v23
	v_mul_f32_e32 v25, v12, v23
	s_waitcnt vmcnt(44)
	v_pk_add_f32 v[26:27], v[176:177], v[178:179]
	v_fma_f32 v24, v12, v22, -v24
	v_fma_f32 v25, v13, v22, v25
	s_add_u32 s50, s46, s48
	s_addc_u32 s51, s47, s49
	s_add_u32 s58, s56, s48
	s_addc_u32 s59, s57, s49
	global_load_dword v144, v10, s[50:51]
	global_load_dword v145, v10, s[50:51] offset:256
	global_load_dword v146, v10, s[58:59]
	global_load_dword v147, v10, s[58:59] offset:256
	v_add_f32_e32 v22, v24, v26
	v_add_f32_e32 v23, v25, v27
	v_mul_f32_e32 v24, v13, v23
	v_mul_f32_e32 v25, v12, v23
	s_waitcnt vmcnt(44)
	v_pk_add_f32 v[26:27], v[180:181], v[182:183]
	v_fma_f32 v24, v12, v22, -v24
	v_fma_f32 v25, v13, v22, v25
	s_add_u32 s52, s50, s48
	s_addc_u32 s53, s51, s49
	s_add_u32 s60, s58, s48
	s_addc_u32 s61, s59, s49
	global_load_dword v148, v10, s[52:53]
	global_load_dword v149, v10, s[52:53] offset:256
	global_load_dword v150, v10, s[60:61]
	global_load_dword v151, v10, s[60:61] offset:256
	v_add_f32_e32 v22, v24, v26
	v_add_f32_e32 v23, v25, v27
	v_mul_f32_e32 v24, v13, v23
	v_mul_f32_e32 v25, v12, v23
	s_waitcnt vmcnt(44)
	v_pk_add_f32 v[26:27], v[104:105], v[106:107]
	v_fma_f32 v24, v12, v22, -v24
	v_fma_f32 v25, v13, v22, v25
	v_add_f32_e32 v22, v24, v26
	v_add_f32_e32 v23, v25, v27
	v_mul_f32_e32 v24, v13, v23
	v_mul_f32_e32 v25, v12, v23
	s_waitcnt vmcnt(40)
	v_pk_add_f32 v[26:27], v[108:109], v[110:111]
	v_fma_f32 v24, v12, v22, -v24
	v_fma_f32 v25, v13, v22, v25
	v_add_f32_e32 v22, v24, v26
	v_add_f32_e32 v23, v25, v27
	v_mul_f32_e32 v24, v13, v23
	v_mul_f32_e32 v25, v12, v23
	s_waitcnt vmcnt(36)
	v_pk_add_f32 v[26:27], v[112:113], v[114:115]
	v_fma_f32 v24, v12, v22, -v24
	v_fma_f32 v25, v13, v22, v25
	v_add_f32_e32 v22, v24, v26
	v_add_f32_e32 v23, v25, v27
	v_mul_f32_e32 v24, v13, v23
	v_mul_f32_e32 v25, v12, v23
	s_waitcnt vmcnt(32)
	v_pk_add_f32 v[26:27], v[116:117], v[118:119]
	v_fma_f32 v24, v12, v22, -v24
	v_fma_f32 v25, v13, v22, v25
	v_add_f32_e32 v22, v24, v26
	v_add_f32_e32 v23, v25, v27
	v_mul_f32_e32 v24, v13, v23
	v_mul_f32_e32 v25, v12, v23
	s_waitcnt vmcnt(28)
	v_pk_add_f32 v[26:27], v[120:121], v[122:123]
	v_fma_f32 v24, v12, v22, -v24
	v_fma_f32 v25, v13, v22, v25
	v_add_f32_e32 v22, v24, v26
	v_add_f32_e32 v23, v25, v27
	v_mul_f32_e32 v24, v13, v23
	v_mul_f32_e32 v25, v12, v23
	s_waitcnt vmcnt(24)
	v_pk_add_f32 v[26:27], v[124:125], v[126:127]
	v_fma_f32 v24, v12, v22, -v24
	v_fma_f32 v25, v13, v22, v25
	v_add_f32_e32 v22, v24, v26
	v_add_f32_e32 v23, v25, v27
	v_mul_f32_e32 v24, v13, v23
	v_mul_f32_e32 v25, v12, v23
	s_waitcnt vmcnt(20)
	v_pk_add_f32 v[26:27], v[128:129], v[130:131]
	v_fma_f32 v24, v12, v22, -v24
	v_fma_f32 v25, v13, v22, v25
	v_add_f32_e32 v22, v24, v26
	v_add_f32_e32 v23, v25, v27
	v_mul_f32_e32 v24, v13, v23
	v_mul_f32_e32 v25, v12, v23
	s_waitcnt vmcnt(16)
	v_pk_add_f32 v[26:27], v[132:133], v[134:135]
	v_fma_f32 v24, v12, v22, -v24
	v_fma_f32 v25, v13, v22, v25
	v_add_f32_e32 v22, v24, v26
	v_add_f32_e32 v23, v25, v27
	v_mul_f32_e32 v24, v13, v23
	v_mul_f32_e32 v25, v12, v23
	s_waitcnt vmcnt(12)
	v_pk_add_f32 v[26:27], v[136:137], v[138:139]
	v_fma_f32 v24, v12, v22, -v24
	v_fma_f32 v25, v13, v22, v25
	v_add_f32_e32 v22, v24, v26
	v_add_f32_e32 v23, v25, v27
	v_mul_f32_e32 v24, v13, v23
	v_mul_f32_e32 v25, v12, v23
	s_waitcnt vmcnt(8)
	v_pk_add_f32 v[26:27], v[140:141], v[142:143]
	v_fma_f32 v24, v12, v22, -v24
	v_fma_f32 v25, v13, v22, v25
	v_add_f32_e32 v22, v24, v26
	v_add_f32_e32 v23, v25, v27
	v_mul_f32_e32 v24, v13, v23
	v_mul_f32_e32 v25, v12, v23
	s_waitcnt vmcnt(4)
	v_pk_add_f32 v[26:27], v[144:145], v[146:147]
	v_fma_f32 v24, v12, v22, -v24
	v_fma_f32 v25, v13, v22, v25
	v_add_f32_e32 v22, v24, v26
	v_add_f32_e32 v23, v25, v27
	v_mul_f32_e32 v24, v13, v23
	v_mul_f32_e32 v25, v12, v23
	s_waitcnt vmcnt(0)
	v_pk_add_f32 v[26:27], v[148:149], v[150:151]
	v_fma_f32 v24, v12, v22, -v24
	v_fma_f32 v25, v13, v22, v25
	v_add_f32_e32 v22, v24, v26
	v_add_f32_e32 v23, v25, v27
	ds_write_b64 v34, v[22:23]

; __device__ __forceinline__ unsigned f2bf(float f) { unsigned u = __builtin_bit_cast(unsigned, f); return (u + 0x7fffu + ((u >> 16) & 1u)) >> 16; }
; __global__ void __launch_bounds__(512, 2) fwd_megakernel(Params Pk) {
;     ...
; #pragma unroll 8
;             for (int i = 0; i < 32; ++i) { const size_t o = (size_t)(cfirst + cstep * i) * 256;
;                 const float er = E[o] + E[o + HALF2], ei = E[o + 64] + E[o + 64 + HALF2];
;                 S[o] = (bf16_t)f2bf(sr); S[o + 64] = (bf16_t)f2bf(si);
;                 const float nr = a.x * sr - a.y * si + er, ni = a.x * si + a.y * sr + ei; sr = nr; si = ni; }
.LBB0_693:
	v_readfirstlane_b32 s44, v24
	v_readfirstlane_b32 s45, v25
	v_readfirstlane_b32 s62, v26
	v_readfirstlane_b32 s63, v27
	s_lshl_b32 s48, s35, 10
	s_ashr_i32 s49, s48, 31
	s_lshl_b32 s70, s35, 9
	s_ashr_i32 s71, s70, 31
	s_add_u32 s44, s44, s0
	s_addc_u32 s45, s45, s1
	s_add_u32 s62, s62, s0
	s_addc_u32 s63, s63, s1
	s_add_u32 s44, s44, 0x9400000
	s_addc_u32 s45, s45, 0
	s_add_u32 s62, s62, 0x4000000
	s_addc_u32 s63, s63, 0
	s_add_u32 s54, s44, s31
	s_addc_u32 s55, s45, 0
	global_load_dword v104, v10, s[44:45]
	global_load_dword v105, v10, s[44:45] offset:256
	global_load_dword v106, v10, s[54:55]
	global_load_dword v107, v10, s[54:55] offset:256
	s_add_u32 s46, s44, s48
	s_addc_u32 s47, s45, s49
	s_add_u32 s56, s54, s48
	s_addc_u32 s57, s55, s49
	global_load_dword v108, v10, s[46:47]
	global_load_dword v109, v10, s[46:47] offset:256
	global_load_dword v110, v10, s[56:57]
	global_load_dword v111, v10, s[56:57] offset:256
	s_add_u32 s50, s46, s48
	s_addc_u32 s51, s47, s49
	s_add_u32 s58, s56, s48
	s_addc_u32 s59, s57, s49
	global_load_dword v112, v10, s[50:51]
	global_load_dword v113, v10, s[50:51] offset:256
	global_load_dword v114, v10, s[58:59]
	global_load_dword v115, v10, s[58:59] offset:256
	s_add_u32 s52, s50, s48
	s_addc_u32 s53, s51, s49
	s_add_u32 s60, s58, s48
	s_addc_u32 s61, s59, s49
	global_load_dword v116, v10, s[52:53]
	global_load_dword v117, v10, s[52:53] offset:256
	global_load_dword v118, v10, s[60:61]
	global_load_dword v119, v10, s[60:61] offset:256
	s_add_u32 s44, s52, s48
	s_addc_u32 s45, s53, s49
	s_add_u32 s54, s60, s48
	s_addc_u32 s55, s61, s49
	global_load_dword v120, v10, s[44:45]
	global_load_dword v121, v10, s[44:45] offset:256
	global_load_dword v122, v10, s[54:55]
	global_load_dword v123, v10, s[54:55] offset:256
	s_add_u32 s46, s44, s48
	s_addc_u32 s47, s45, s49
	s_add_u32 s56, s54, s48
	s_addc_u32 s57, s55, s49
	global_load_dword v124, v10, s[46:47]
	global_load_dword v125, v10, s[46:47] offset:256
	global_load_dword v126, v10, s[56:57]
	global_load_dword v127, v10, s[56:57] offset:256
	s_add_u32 s50, s46, s48
	s_addc_u32 s51, s47, s49
	s_add_u32 s58, s56, s48
	s_addc_u32 s59, s57, s49
	global_load_dword v128, v10, s[50:51]
	global_load_dword v129, v10, s[50:51] offset:256
	global_load_dword v130, v10, s[58:59]
	global_load_dword v131, v10, s[58:59] offset:256
	s_add_u32 s52, s50, s48
	s_addc_u32 s53, s51, s49
	s_add_u32 s60, s58, s48
	s_addc_u32 s61, s59, s49
	global_load_dword v132, v10, s[52:53]
	global_load_dword v133, v10, s[52:53] offset:256
	global_load_dword v134, v10, s[60:61]
	global_load_dword v135, v10, s[60:61] offset:256
	s_add_u32 s44, s52, s48
	s_addc_u32 s45, s53, s49
	s_add_u32 s54, s60, s48
	s_addc_u32 s55, s61, s49
	global_load_dword v136, v10, s[44:45]
	global_load_dword v137, v10, s[44:45] offset:256
	global_load_dword v138, v10, s[54:55]
	global_load_dword v139, v10, s[54:55] offset:256
	s_add_u32 s46, s44, s48
	s_addc_u32 s47, s45, s49
	s_add_u32 s56, s54, s48
	s_addc_u32 s57, s55, s49
	global_load_dword v140, v10, s[46:47]
	global_load_dword v141, v10, s[46:47] offset:256
	global_load_dword v142, v10, s[56:57]
	global_load_dword v143, v10, s[56:57] offset:256
	s_add_u32 s50, s46, s48
	s_addc_u32 s51, s47, s49
	s_add_u32 s58, s56, s48
	s_addc_u32 s59, s57, s49
	global_load_dword v144, v10, s[50:51]
	global_load_dword v145, v10, s[50:51] offset:256
	global_load_dword v146, v10, s[58:59]
	global_load_dword v147, v10, s[58:59] offset:256
	s_add_u32 s52, s50, s48
	s_addc_u32 s53, s51, s49
	s_add_u32 s60, s58, s48
	s_addc_u32 s61, s59, s49
	global_load_dword v148, v10, s[52:53]
	global_load_dword v149, v10, s[52:53] offset:256
	global_load_dword v150, v10, s[60:61]
	global_load_dword v151, v10, s[60:61] offset:256
	v_bfe_u32 v184, v20, 16, 1
	v_bfe_u32 v185, v21, 16, 1
	v_mul_f32_e32 v24, v18, v21
	v_add3_u32 v184, v20, v184, s34
	v_add3_u32 v185, v21, v185, s34
	v_mul_f32_e32 v25, v18, v20
	global_store_short_d16_hi v8, v184, s[62:63]
	global_store_short_d16_hi v8, v185, s[62:63] offset:128
	s_waitcnt vmcnt(46)
	v_pk_add_f32 v[26:27], v[104:105], v[106:107]
	v_fma_f32 v24, v12, v20, -v24
	v_fma_f32 v25, v12, v21, v25
	s_add_u32 s44, s52, s48
	s_addc_u32 s45, s53, s49
	s_add_u32 s54, s60, s48
	s_addc_u32 s55, s61, s49
	global_load_dword v152, v10, s[44:45]
	global_load_dword v153, v10, s[44:45] offset:256
	global_load_dword v154, v10, s[54:55]
	global_load_dword v155, v10, s[54:55] offset:256
	v_add_f32_e32 v20, v24, v26
	v_add_f32_e32 v21, v25, v27
	s_add_u32 s64, s62, s70
	s_addc_u32 s65, s63, s71
	v_bfe_u32 v186, v20, 16, 1
	v_bfe_u32 v187, v21, 16, 1
	v_mul_f32_e32 v24, v18, v21
	v_add3_u32 v186, v20, v186, s34
	v_add3_u32 v187, v21, v187, s34
	v_mul_f32_e32 v25, v18, v20
	global_store_short_d16_hi v8, v186, s[64:65]
	global_store_short_d16_hi v8, v187, s[64:65] offset:128
	s_waitcnt vmcnt(48)
	v_pk_add_f32 v[26:27], v[108:109], v[110:111]
	v_fma_f32 v24, v12, v20, -v24
	v_fma_f32 v25, v12, v21, v25
	s_add_u32 s46, s44, s48
	s_addc_u32 s47, s45, s49
	s_add_u32 s56, s54, s48
	s_addc_u32 s57, s55, s49
	global_load_dword v156, v10, s[46:47]
	global_load_dword v157, v10, s[46:47] offset:256
	global_load_dword v158, v10, s[56:57]
	global_load_dword v159, v10, s[56:57] offset:256
	v_add_f32_e32 v20, v24, v26
	v_add_f32_e32 v21, v25, v27
	s_add_u32 s66, s64, s70
	s_addc_u32 s67, s65, s71
	v_bfe_u32 v184, v20, 16, 1
	v_bfe_u32 v185, v21, 16, 1
	v_mul_f32_e32 v24, v18, v21
	v_add3_u32 v184, v20, v184, s34
	v_add3_u32 v185, v21, v185, s34
	v_mul_f32_e32 v25, v18, v20
	global_store_short_d16_hi v8, v184, s[66:67]
	global_store_short_d16_hi v8, v185, s[66:67] offset:128
	s_waitcnt vmcnt(50)
; __device__ __forceinline__ unsigned f2bf(float f) { unsigned u = __builtin_bit_cast(unsigned, f); return (u + 0x7fffu + ((u >> 16) & 1u)) >> 16; }
; __global__ void __launch_bounds__(512, 2) fwd_megakernel(Params Pk) {
;     ...
; #pragma unroll 8
;             for (int i = 0; i < 32; ++i) { const size_t o = (size_t)(cfirst + cstep * i) * 256;
;                 const float er = E[o] + E[o + HALF2], ei = E[o + 64] + E[o + 64 + HALF2];
;                 S[o] = (bf16_t)f2bf(sr); S[o + 64] = (bf16_t)f2bf(si);
;                 const float nr = a.x * sr - a.y * si + er, ni = a.x * si + a.y * sr + ei; sr = nr; si = ni; }
	v_pk_add_f32 v[26:27], v[112:113], v[114:115]
	v_fma_f32 v24, v12, v20, -v24
	v_fma_f32 v25, v12, v21, v25
	s_add_u32 s50, s46, s48
	s_addc_u32 s51, s47, s49
	s_add_u32 s58, s56, s48
	s_addc_u32 s59, s57, s49
	global_load_dword v160, v10, s[50:51]
	global_load_dword v161, v10, s[50:51] offset:256
	global_load_dword v162, v10, s[58:59]
	global_load_dword v163, v10, s[58:59] offset:256
	v_add_f32_e32 v20, v24, v26
	v_add_f32_e32 v21, v25, v27
	s_add_u32 s68, s66, s70
	s_addc_u32 s69, s67, s71
	v_bfe_u32 v186, v20, 16, 1
	v_bfe_u32 v187, v21, 16, 1
	v_mul_f32_e32 v24, v18, v21
	v_add3_u32 v186, v20, v186, s34
	v_add3_u32 v187, v21, v187, s34
	v_mul_f32_e32 v25, v18, v20
	global_store_short_d16_hi v8, v186, s[68:69]
	global_store_short_d16_hi v8, v187, s[68:69] offset:128
	s_waitcnt vmcnt(52)
	v_pk_add_f32 v[26:27], v[116:117], v[118:119]
	v_fma_f32 v24, v12, v20, -v24
	v_fma_f32 v25, v12, v21, v25
	s_add_u32 s52, s50, s48
	s_addc_u32 s53, s51, s49
	s_add_u32 s60, s58, s48
	s_addc_u32 s61, s59, s49
	global_load_dword v164, v10, s[52:53]
	global_load_dword v165, v10, s[52:53] offset:256
	global_load_dword v166, v10, s[60:61]
	global_load_dword v167, v10, s[60:61] offset:256
	v_add_f32_e32 v20, v24, v26
	v_add_f32_e32 v21, v25, v27
	s_add_u32 s62, s68, s70
	s_addc_u32 s63, s69, s71
	v_bfe_u32 v184, v20, 16, 1
	v_bfe_u32 v185, v21, 16, 1
	v_mul_f32_e32 v24, v18, v21
	v_add3_u32 v184, v20, v184, s34
	v_add3_u32 v185, v21, v185, s34
	v_mul_f32_e32 v25, v18, v20
	global_store_short_d16_hi v8, v184, s[62:63]
	global_store_short_d16_hi v8, v185, s[62:63] offset:128
	s_waitcnt vmcnt(54)
	v_pk_add_f32 v[26:27], v[120:121], v[122:123]
	v_fma_f32 v24, v12, v20, -v24
	v_fma_f32 v25, v12, v21, v25
	s_add_u32 s44, s52, s48
	s_addc_u32 s45, s53, s49
	s_add_u32 s54, s60, s48
	s_addc_u32 s55, s61, s49
	global_load_dword v168, v10, s[44:45]
	global_load_dword v169, v10, s[44:45] offset:256
	global_load_dword v170, v10, s[54:55]
	global_load_dword v171, v10, s[54:55] offset:256
	v_add_f32_e32 v20, v24, v26
	v_add_f32_e32 v21, v25, v27
	s_add_u32 s64, s62, s70
	s_addc_u32 s65, s63, s71
	v_bfe_u32 v186, v20, 16, 1
	v_bfe_u32 v187, v21, 16, 1
	v_mul_f32_e32 v24, v18, v21
	v_add3_u32 v186, v20, v186, s34
	v_add3_u32 v187, v21, v187, s34
	v_mul_f32_e32 v25, v18, v20
	global_store_short_d16_hi v8, v186, s[64:65]
	global_store_short_d16_hi v8, v187, s[64:65] offset:128
	s_waitcnt vmcnt(56)
	v_pk_add_f32 v[26:27], v[124:125], v[126:127]
	v_fma_f32 v24, v12, v20, -v24
	v_fma_f32 v25, v12, v21, v25
	s_add_u32 s46, s44, s48
	s_addc_u32 s47, s45, s49
	s_add_u32 s56, s54, s48
	s_addc_u32 s57, s55, s49
	global_load_dword v172, v10, s[46:47]
	global_load_dword v173, v10, s[46:47] offset:256
	global_load_dword v174, v10, s[56:57]
	global_load_dword v175, v10, s[56:57] offset:256
	v_add_f32_e32 v20, v24, v26
	v_add_f32_e32 v21, v25, v27
	s_add_u32 s66, s64, s70
	s_addc_u32 s67, s65, s71
	v_bfe_u32 v184, v20, 16, 1
	v_bfe_u32 v185, v21, 16, 1
	v_mul_f32_e32 v24, v18, v21
	v_add3_u32 v184, v20, v184, s34
	v_add3_u32 v185, v21, v185, s34
	v_mul_f32_e32 v25, v18, v20
	global_store_short_d16_hi v8, v184, s[66:67]
	global_store_short_d16_hi v8, v185, s[66:67] offset:128
	s_waitcnt vmcnt(58)
	v_pk_add_f32 v[26:27], v[128:129], v[130:131]
	v_fma_f32 v24, v12, v20, -v24
	v_fma_f32 v25, v12, v21, v25
	s_add_u32 s50, s46, s48
	s_addc_u32 s51, s47, s49
	s_add_u32 s58, s56, s48
	s_addc_u32 s59, s57, s49
	global_load_dword v176, v10, s[50:51]
	global_load_dword v177, v10, s[50:51] offset:256
	global_load_dword v178, v10, s[58:59]
	global_load_dword v179, v10, s[58:59] offset:256
	v_add_f32_e32 v20, v24, v26
	v_add_f32_e32 v21, v25, v27
	s_add_u32 s68, s66, s70
	s_addc_u32 s69, s67, s71
	v_bfe_u32 v186, v20, 16, 1
	v_bfe_u32 v187, v21, 16, 1
	v_mul_f32_e32 v24, v18, v21
	v_add3_u32 v186, v20, v186, s34
	v_add3_u32 v187, v21, v187, s34
	v_mul_f32_e32 v25, v18, v20
	s_waitcnt vmcnt(61)
	global_store_short_d16_hi v8, v186, s[68:69]
	global_store_short_d16_hi v8, v187, s[68:69] offset:128
	s_waitcnt vmcnt(60)
	v_pk_add_f32 v[26:27], v[132:133], v[134:135]
	v_fma_f32 v24, v12, v20, -v24
	v_fma_f32 v25, v12, v21, v25
	s_add_u32 s52, s50, s48
	s_addc_u32 s53, s51, s49
	s_add_u32 s60, s58, s48
	s_addc_u32 s61, s59, s49
	s_waitcnt vmcnt(59)
	global_load_dword v180, v10, s[52:53]
	global_load_dword v181, v10, s[52:53] offset:256
	global_load_dword v182, v10, s[60:61]
	global_load_dword v183, v10, s[60:61] offset:256
	v_add_f32_e32 v20, v24, v26
	v_add_f32_e32 v21, v25, v27
	s_add_u32 s62, s68, s70
	s_addc_u32 s63, s69, s71
	v_bfe_u32 v184, v20, 16, 1
	v_bfe_u32 v185, v21, 16, 1
	v_mul_f32_e32 v24, v18, v21
	v_add3_u32 v184, v20, v184, s34
	v_add3_u32 v185, v21, v185, s34
	v_mul_f32_e32 v25, v18, v20
	s_waitcnt vmcnt(61)
	global_store_short_d16_hi v8, v184, s[62:63]
	global_store_short_d16_hi v8, v185, s[62:63] offset:128
	s_waitcnt vmcnt(62)
	v_pk_add_f32 v[26:27], v[136:137], v[138:139]
	v_fma_f32 v24, v12, v20, -v24
	v_fma_f32 v25, v12, v21, v25
	s_add_u32 s44, s52, s48
	s_addc_u32 s45, s53, s49
	s_add_u32 s54, s60, s48
	s_addc_u32 s55, s61, s49
	s_waitcnt vmcnt(59)
	global_load_dword v104, v10, s[44:45]
	global_load_dword v105, v10, s[44:45] offset:256
	global_load_dword v106, v10, s[54:55]
	global_load_dword v107, v10, s[54:55] offset:256
	v_add_f32_e32 v20, v24, v26
	v_add_f32_e32 v21, v25, v27
	s_add_u32 s64, s62, s70
	s_addc_u32 s65, s63, s71
	v_bfe_u32 v186, v20, 16, 1
	v_bfe_u32 v187, v21, 16, 1
	v_mul_f32_e32 v24, v18, v21
	v_add3_u32 v186, v20, v186, s34
	v_add3_u32 v187, v21, v187, s34
	v_mul_f32_e32 v25, v18, v20
	s_waitcnt vmcnt(61)
; __device__ __forceinline__ unsigned f2bf(float f) { unsigned u = __builtin_bit_cast(unsigned, f); return (u + 0x7fffu + ((u >> 16) & 1u)) >> 16; }
; __global__ void __launch_bounds__(512, 2) fwd_megakernel(Params Pk) {
;     ...
; #pragma unroll 8
;             for (int i = 0; i < 32; ++i) { const size_t o = (size_t)(cfirst + cstep * i) * 256;
;                 const float er = E[o] + E[o + HALF2], ei = E[o + 64] + E[o + 64 + HALF2];
;                 S[o] = (bf16_t)f2bf(sr); S[o + 64] = (bf16_t)f2bf(si);
;                 const float nr = a.x * sr - a.y * si + er, ni = a.x * si + a.y * sr + ei; sr = nr; si = ni; }
	global_store_short_d16_hi v8, v186, s[64:65]
	global_store_short_d16_hi v8, v187, s[64:65] offset:128
	v_pk_add_f32 v[26:27], v[140:141], v[142:143]
	v_fma_f32 v24, v12, v20, -v24
	v_fma_f32 v25, v12, v21, v25
	s_add_u32 s46, s44, s48
	s_addc_u32 s47, s45, s49
	s_add_u32 s56, s54, s48
	s_addc_u32 s57, s55, s49
	s_waitcnt vmcnt(59)
	global_load_dword v108, v10, s[46:47]
	global_load_dword v109, v10, s[46:47] offset:256
	global_load_dword v110, v10, s[56:57]
	global_load_dword v111, v10, s[56:57] offset:256
	v_add_f32_e32 v20, v24, v26
	v_add_f32_e32 v21, v25, v27
	s_add_u32 s66, s64, s70
	s_addc_u32 s67, s65, s71
	v_bfe_u32 v184, v20, 16, 1
	v_bfe_u32 v185, v21, 16, 1
	v_mul_f32_e32 v24, v18, v21
	v_add3_u32 v184, v20, v184, s34
	v_add3_u32 v185, v21, v185, s34
	v_mul_f32_e32 v25, v18, v20
	s_waitcnt vmcnt(61)
	global_store_short_d16_hi v8, v184, s[66:67]
	global_store_short_d16_hi v8, v185, s[66:67] offset:128
	v_pk_add_f32 v[26:27], v[144:145], v[146:147]
	v_fma_f32 v24, v12, v20, -v24
	v_fma_f32 v25, v12, v21, v25
	s_add_u32 s50, s46, s48
	s_addc_u32 s51, s47, s49
	s_add_u32 s58, s56, s48
	s_addc_u32 s59, s57, s49
	s_waitcnt vmcnt(59)
	global_load_dword v112, v10, s[50:51]
	global_load_dword v113, v10, s[50:51] offset:256
	global_load_dword v114, v10, s[58:59]
	global_load_dword v115, v10, s[58:59] offset:256
	v_add_f32_e32 v20, v24, v26
	v_add_f32_e32 v21, v25, v27
	s_add_u32 s68, s66, s70
	s_addc_u32 s69, s67, s71
	v_bfe_u32 v186, v20, 16, 1
	v_bfe_u32 v187, v21, 16, 1
	v_mul_f32_e32 v24, v18, v21
	v_add3_u32 v186, v20, v186, s34
	v_add3_u32 v187, v21, v187, s34
	v_mul_f32_e32 v25, v18, v20
	s_waitcnt vmcnt(61)
	global_store_short_d16_hi v8, v186, s[68:69]
	global_store_short_d16_hi v8, v187, s[68:69] offset:128
	v_pk_add_f32 v[26:27], v[148:149], v[150:151]
	v_fma_f32 v24, v12, v20, -v24
	v_fma_f32 v25, v12, v21, v25
	s_add_u32 s52, s50, s48
	s_addc_u32 s53, s51, s49
	s_add_u32 s60, s58, s48
	s_addc_u32 s61, s59, s49
	s_waitcnt vmcnt(59)
	global_load_dword v116, v10, s[52:53]
	global_load_dword v117, v10, s[52:53] offset:256
	global_load_dword v118, v10, s[60:61]
	global_load_dword v119, v10, s[60:61] offset:256
	v_add_f32_e32 v20, v24, v26
	v_add_f32_e32 v21, v25, v27
	s_add_u32 s62, s68, s70
	s_addc_u32 s63, s69, s71
	v_bfe_u32 v184, v20, 16, 1
	v_bfe_u32 v185, v21, 16, 1
	v_mul_f32_e32 v24, v18, v21
	v_add3_u32 v184, v20, v184, s34
	v_add3_u32 v185, v21, v185, s34
	v_mul_f32_e32 v25, v18, v20
	s_waitcnt vmcnt(61)
	global_store_short_d16_hi v8, v184, s[62:63]
	global_store_short_d16_hi v8, v185, s[62:63] offset:128
	v_pk_add_f32 v[26:27], v[152:153], v[154:155]
	v_fma_f32 v24, v12, v20, -v24
	v_fma_f32 v25, v12, v21, v25
	s_add_u32 s44, s52, s48
	s_addc_u32 s45, s53, s49
	s_add_u32 s54, s60, s48
	s_addc_u32 s55, s61, s49
	s_waitcnt vmcnt(59)
	global_load_dword v120, v10, s[44:45]
	global_load_dword v121, v10, s[44:45] offset:256
	global_load_dword v122, v10, s[54:55]
	global_load_dword v123, v10, s[54:55] offset:256
	v_add_f32_e32 v20, v24, v26
	v_add_f32_e32 v21, v25, v27
	s_add_u32 s64, s62, s70
	s_addc_u32 s65, s63, s71
	v_bfe_u32 v186, v20, 16, 1
	v_bfe_u32 v187, v21, 16, 1
	v_mul_f32_e32 v24, v18, v21
	v_add3_u32 v186, v20, v186, s34
	v_add3_u32 v187, v21, v187, s34
	v_mul_f32_e32 v25, v18, v20
	s_waitcnt vmcnt(61)
	global_store_short_d16_hi v8, v186, s[64:65]
	global_store_short_d16_hi v8, v187, s[64:65] offset:128
	v_pk_add_f32 v[26:27], v[156:157], v[158:159]
	v_fma_f32 v24, v12, v20, -v24
	v_fma_f32 v25, v12, v21, v25
	s_add_u32 s46, s44, s48
	s_addc_u32 s47, s45, s49
	s_add_u32 s56, s54, s48
	s_addc_u32 s57, s55, s49
	s_waitcnt vmcnt(59)
	global_load_dword v124, v10, s[46:47]
	global_load_dword v125, v10, s[46:47] offset:256
	global_load_dword v126, v10, s[56:57]
	global_load_dword v127, v10, s[56:57] offset:256
	v_add_f32_e32 v20, v24, v26
	v_add_f32_e32 v21, v25, v27
	s_add_u32 s66, s64, s70
	s_addc_u32 s67, s65, s71
	v_bfe_u32 v184, v20, 16, 1
	v_bfe_u32 v185, v21, 16, 1
	v_mul_f32_e32 v24, v18, v21
	v_add3_u32 v184, v20, v184, s34
	v_add3_u32 v185, v21, v185, s34
	v_mul_f32_e32 v25, v18, v20
	s_waitcnt vmcnt(61)
	global_store_short_d16_hi v8, v184, s[66:67]
	global_store_short_d16_hi v8, v185, s[66:67] offset:128
	v_pk_add_f32 v[26:27], v[160:161], v[162:163]
	v_fma_f32 v24, v12, v20, -v24
	v_fma_f32 v25, v12, v21, v25
	s_add_u32 s50, s46, s48
	s_addc_u32 s51, s47, s49
	s_add_u32 s58, s56, s48
	s_addc_u32 s59, s57, s49
	s_waitcnt vmcnt(59)
	global_load_dword v128, v10, s[50:51]
	global_load_dword v129, v10, s[50:51] offset:256
	global_load_dword v130, v10, s[58:59]
	global_load_dword v131, v10, s[58:59] offset:256
	v_add_f32_e32 v20, v24, v26
	v_add_f32_e32 v21, v25, v27
	s_add_u32 s68, s66, s70
	s_addc_u32 s69, s67, s71
	v_bfe_u32 v186, v20, 16, 1
	v_bfe_u32 v187, v21, 16, 1
	v_mul_f32_e32 v24, v18, v21
	v_add3_u32 v186, v20, v186, s34
	v_add3_u32 v187, v21, v187, s34
	v_mul_f32_e32 v25, v18, v20
	s_waitcnt vmcnt(61)
	global_store_short_d16_hi v8, v186, s[68:69]
	global_store_short_d16_hi v8, v187, s[68:69] offset:128
	v_pk_add_f32 v[26:27], v[164:165], v[166:167]
	v_fma_f32 v24, v12, v20, -v24
	v_fma_f32 v25, v12, v21, v25
	s_add_u32 s52, s50, s48
	s_addc_u32 s53, s51, s49
	s_add_u32 s60, s58, s48
	s_addc_u32 s61, s59, s49
	s_waitcnt vmcnt(59)
	global_load_dword v132, v10, s[52:53]
	global_load_dword v133, v10, s[52:53] offset:256
	global_load_dword v134, v10, s[60:61]
	global_load_dword v135, v10, s[60:61] offset:256
	v_add_f32_e32 v20, v24, v26
	v_add_f32_e32 v21, v25, v27
	s_add_u32 s62, s68, s70
	s_addc_u32 s63, s69, s71
	v_bfe_u32 v184, v20, 16, 1
	v_bfe_u32 v185, v21, 16, 1
	v_mul_f32_e32 v24, v18, v21
	v_add3_u32 v184, v20, v184, s34
	v_add3_u32 v185, v21, v185, s34
	v_mul_f32_e32 v25, v18, v20
	s_waitcnt vmcnt(61)
; __device__ __forceinline__ unsigned f2bf(float f) { unsigned u = __builtin_bit_cast(unsigned, f); return (u + 0x7fffu + ((u >> 16) & 1u)) >> 16; }
; __global__ void __launch_bounds__(512, 2) fwd_megakernel(Params Pk) {
;     ...
; #pragma unroll 8
;             for (int i = 0; i < 32; ++i) { const size_t o = (size_t)(cfirst + cstep * i) * 256;
;                 const float er = E[o] + E[o + HALF2], ei = E[o + 64] + E[o + 64 + HALF2];
;                 S[o] = (bf16_t)f2bf(sr); S[o + 64] = (bf16_t)f2bf(si);
;                 const float nr = a.x * sr - a.y * si + er, ni = a.x * si + a.y * sr + ei; sr = nr; si = ni; }
	global_store_short_d16_hi v8, v184, s[62:63]
	global_store_short_d16_hi v8, v185, s[62:63] offset:128
	v_pk_add_f32 v[26:27], v[168:169], v[170:171]
	v_fma_f32 v24, v12, v20, -v24
	v_fma_f32 v25, v12, v21, v25
	s_add_u32 s44, s52, s48
	s_addc_u32 s45, s53, s49
	s_add_u32 s54, s60, s48
	s_addc_u32 s55, s61, s49
	s_waitcnt vmcnt(59)
	global_load_dword v136, v10, s[44:45]
	global_load_dword v137, v10, s[44:45] offset:256
	global_load_dword v138, v10, s[54:55]
	global_load_dword v139, v10, s[54:55] offset:256
	v_add_f32_e32 v20, v24, v26
	v_add_f32_e32 v21, v25, v27
	s_add_u32 s64, s62, s70
	s_addc_u32 s65, s63, s71
	v_bfe_u32 v186, v20, 16, 1
	v_bfe_u32 v187, v21, 16, 1
	v_mul_f32_e32 v24, v18, v21
	v_add3_u32 v186, v20, v186, s34
	v_add3_u32 v187, v21, v187, s34
	v_mul_f32_e32 v25, v18, v20
	s_waitcnt vmcnt(61)
	global_store_short_d16_hi v8, v186, s[64:65]
	global_store_short_d16_hi v8, v187, s[64:65] offset:128
	v_pk_add_f32 v[26:27], v[172:173], v[174:175]
	v_fma_f32 v24, v12, v20, -v24
	v_fma_f32 v25, v12, v21, v25
	s_add_u32 s46, s44, s48
	s_addc_u32 s47, s45, s49
	s_add_u32 s56, s54, s48
	s_addc_u32 s57, s55, s49
	s_waitcnt vmcnt(59)
	global_load_dword v140, v10, s[46:47]
	global_load_dword v141, v10, s[46:47] offset:256
	global_load_dword v142, v10, s[56:57]
	global_load_dword v143, v10, s[56:57] offset:256
	v_add_f32_e32 v20, v24, v26
	v_add_f32_e32 v21, v25, v27
	s_add_u32 s66, s64, s70
	s_addc_u32 s67, s65, s71
	v_bfe_u32 v184, v20, 16, 1
	v_bfe_u32 v185, v21, 16, 1
	v_mul_f32_e32 v24, v18, v21
	v_add3_u32 v184, v20, v184, s34
	v_add3_u32 v185, v21, v185, s34
	v_mul_f32_e32 v25, v18, v20
	s_waitcnt vmcnt(61)
	global_store_short_d16_hi v8, v184, s[66:67]
	global_store_short_d16_hi v8, v185, s[66:67] offset:128
	v_pk_add_f32 v[26:27], v[176:177], v[178:179]
	v_fma_f32 v24, v12, v20, -v24
	v_fma_f32 v25, v12, v21, v25
	s_add_u32 s50, s46, s48
	s_addc_u32 s51, s47, s49
	s_add_u32 s58, s56, s48
	s_addc_u32 s59, s57, s49
	s_waitcnt vmcnt(59)
	global_load_dword v144, v10, s[50:51]
	global_load_dword v145, v10, s[50:51] offset:256
	global_load_dword v146, v10, s[58:59]
	global_load_dword v147, v10, s[58:59] offset:256
	v_add_f32_e32 v20, v24, v26
	v_add_f32_e32 v21, v25, v27
	s_add_u32 s68, s66, s70
	s_addc_u32 s69, s67, s71
	v_bfe_u32 v186, v20, 16, 1
	v_bfe_u32 v187, v21, 16, 1
	v_mul_f32_e32 v24, v18, v21
	v_add3_u32 v186, v20, v186, s34
	v_add3_u32 v187, v21, v187, s34
	v_mul_f32_e32 v25, v18, v20
	s_waitcnt vmcnt(61)
	global_store_short_d16_hi v8, v186, s[68:69]
	global_store_short_d16_hi v8, v187, s[68:69] offset:128
	v_pk_add_f32 v[26:27], v[180:181], v[182:183]
	v_fma_f32 v24, v12, v20, -v24
	v_fma_f32 v25, v12, v21, v25
	s_add_u32 s52, s50, s48
	s_addc_u32 s53, s51, s49
	s_add_u32 s60, s58, s48
	s_addc_u32 s61, s59, s49
	s_waitcnt vmcnt(59)
	global_load_dword v148, v10, s[52:53]
	global_load_dword v149, v10, s[52:53] offset:256
	global_load_dword v150, v10, s[60:61]
	global_load_dword v151, v10, s[60:61] offset:256
	v_add_f32_e32 v20, v24, v26
	v_add_f32_e32 v21, v25, v27
	s_add_u32 s62, s68, s70
	s_addc_u32 s63, s69, s71
	v_bfe_u32 v184, v20, 16, 1
	v_bfe_u32 v185, v21, 16, 1
	v_mul_f32_e32 v24, v18, v21
	v_add3_u32 v184, v20, v184, s34
	v_add3_u32 v185, v21, v185, s34
	v_mul_f32_e32 v25, v18, v20
	s_waitcnt vmcnt(61)
	global_store_short_d16_hi v8, v184, s[62:63]
	global_store_short_d16_hi v8, v185, s[62:63] offset:128
	v_pk_add_f32 v[26:27], v[104:105], v[106:107]
	v_fma_f32 v24, v12, v20, -v24
	v_fma_f32 v25, v12, v21, v25
	v_add_f32_e32 v20, v24, v26
	v_add_f32_e32 v21, v25, v27
	s_add_u32 s64, s62, s70
	s_addc_u32 s65, s63, s71
	v_bfe_u32 v186, v20, 16, 1
	v_bfe_u32 v187, v21, 16, 1
	v_mul_f32_e32 v24, v18, v21
	v_add3_u32 v186, v20, v186, s34
	v_add3_u32 v187, v21, v187, s34
	v_mul_f32_e32 v25, v18, v20
	s_waitcnt vmcnt(61)
	global_store_short_d16_hi v8, v186, s[64:65]
	global_store_short_d16_hi v8, v187, s[64:65] offset:128
	v_pk_add_f32 v[26:27], v[108:109], v[110:111]
	v_fma_f32 v24, v12, v20, -v24
	v_fma_f32 v25, v12, v21, v25
	v_add_f32_e32 v20, v24, v26
	v_add_f32_e32 v21, v25, v27
	s_add_u32 s66, s64, s70
	s_addc_u32 s67, s65, s71
	v_bfe_u32 v184, v20, 16, 1
	v_bfe_u32 v185, v21, 16, 1
	v_mul_f32_e32 v24, v18, v21
	v_add3_u32 v184, v20, v184, s34
	v_add3_u32 v185, v21, v185, s34
	v_mul_f32_e32 v25, v18, v20
	s_waitcnt vmcnt(61)
	global_store_short_d16_hi v8, v184, s[66:67]
	global_store_short_d16_hi v8, v185, s[66:67] offset:128
	s_waitcnt vmcnt(60)
; __device__ __forceinline__ unsigned f2bf(float f) { unsigned u = __builtin_bit_cast(unsigned, f); return (u + 0x7fffu + ((u >> 16) & 1u)) >> 16; }
; __global__ void __launch_bounds__(512, 2) fwd_megakernel(Params Pk) {
;     ...
; #pragma unroll 8
;             for (int i = 0; i < 32; ++i) { const size_t o = (size_t)(cfirst + cstep * i) * 256;
;                 const float er = E[o] + E[o + HALF2], ei = E[o + 64] + E[o + 64 + HALF2];
;                 S[o] = (bf16_t)f2bf(sr); S[o + 64] = (bf16_t)f2bf(si);
;                 const float nr = a.x * sr - a.y * si + er, ni = a.x * si + a.y * sr + ei; sr = nr; si = ni; }
;             __syncthreads();
;         }
	v_pk_add_f32 v[26:27], v[112:113], v[114:115]
	v_fma_f32 v24, v12, v20, -v24
	v_fma_f32 v25, v12, v21, v25
	v_add_f32_e32 v20, v24, v26
	v_add_f32_e32 v21, v25, v27
	s_add_u32 s68, s66, s70
	s_addc_u32 s69, s67, s71
	v_bfe_u32 v186, v20, 16, 1
	v_bfe_u32 v187, v21, 16, 1
	v_mul_f32_e32 v24, v18, v21
	v_add3_u32 v186, v20, v186, s34
	v_add3_u32 v187, v21, v187, s34
	v_mul_f32_e32 v25, v18, v20
	global_store_short_d16_hi v8, v186, s[68:69]
	global_store_short_d16_hi v8, v187, s[68:69] offset:128
	s_waitcnt vmcnt(56)
	v_pk_add_f32 v[26:27], v[116:117], v[118:119]
	v_fma_f32 v24, v12, v20, -v24
	v_fma_f32 v25, v12, v21, v25
	v_add_f32_e32 v20, v24, v26
	v_add_f32_e32 v21, v25, v27
	s_add_u32 s62, s68, s70
	s_addc_u32 s63, s69, s71
	v_bfe_u32 v184, v20, 16, 1
	v_bfe_u32 v185, v21, 16, 1
	v_mul_f32_e32 v24, v18, v21
	v_add3_u32 v184, v20, v184, s34
	v_add3_u32 v185, v21, v185, s34
	v_mul_f32_e32 v25, v18, v20
	global_store_short_d16_hi v8, v184, s[62:63]
	global_store_short_d16_hi v8, v185, s[62:63] offset:128
	s_waitcnt vmcnt(52)
	v_pk_add_f32 v[26:27], v[120:121], v[122:123]
	v_fma_f32 v24, v12, v20, -v24
	v_fma_f32 v25, v12, v21, v25
	v_add_f32_e32 v20, v24, v26
	v_add_f32_e32 v21, v25, v27
	s_add_u32 s64, s62, s70
	s_addc_u32 s65, s63, s71
	v_bfe_u32 v186, v20, 16, 1
	v_bfe_u32 v187, v21, 16, 1
	v_mul_f32_e32 v24, v18, v21
	v_add3_u32 v186, v20, v186, s34
	v_add3_u32 v187, v21, v187, s34
	v_mul_f32_e32 v25, v18, v20
	global_store_short_d16_hi v8, v186, s[64:65]
	global_store_short_d16_hi v8, v187, s[64:65] offset:128
	s_waitcnt vmcnt(48)
	v_pk_add_f32 v[26:27], v[124:125], v[126:127]
	v_fma_f32 v24, v12, v20, -v24
	v_fma_f32 v25, v12, v21, v25
	v_add_f32_e32 v20, v24, v26
	v_add_f32_e32 v21, v25, v27
	s_add_u32 s66, s64, s70
	s_addc_u32 s67, s65, s71
	v_bfe_u32 v184, v20, 16, 1
	v_bfe_u32 v185, v21, 16, 1
	v_mul_f32_e32 v24, v18, v21
	v_add3_u32 v184, v20, v184, s34
	v_add3_u32 v185, v21, v185, s34
	v_mul_f32_e32 v25, v18, v20
	global_store_short_d16_hi v8, v184, s[66:67]
	global_store_short_d16_hi v8, v185, s[66:67] offset:128
	s_waitcnt vmcnt(44)
	v_pk_add_f32 v[26:27], v[128:129], v[130:131]
	v_fma_f32 v24, v12, v20, -v24
	v_fma_f32 v25, v12, v21, v25
	v_add_f32_e32 v20, v24, v26
	v_add_f32_e32 v21, v25, v27
	s_add_u32 s68, s66, s70
	s_addc_u32 s69, s67, s71
	v_bfe_u32 v186, v20, 16, 1
	v_bfe_u32 v187, v21, 16, 1
	v_mul_f32_e32 v24, v18, v21
	v_add3_u32 v186, v20, v186, s34
	v_add3_u32 v187, v21, v187, s34
	v_mul_f32_e32 v25, v18, v20
	global_store_short_d16_hi v8, v186, s[68:69]
	global_store_short_d16_hi v8, v187, s[68:69] offset:128
	s_waitcnt vmcnt(40)
	v_pk_add_f32 v[26:27], v[132:133], v[134:135]
	v_fma_f32 v24, v12, v20, -v24
	v_fma_f32 v25, v12, v21, v25
	v_add_f32_e32 v20, v24, v26
	v_add_f32_e32 v21, v25, v27
	s_add_u32 s62, s68, s70
	s_addc_u32 s63, s69, s71
	v_bfe_u32 v184, v20, 16, 1
	v_bfe_u32 v185, v21, 16, 1
	v_mul_f32_e32 v24, v18, v21
	v_add3_u32 v184, v20, v184, s34
	v_add3_u32 v185, v21, v185, s34
	v_mul_f32_e32 v25, v18, v20
	global_store_short_d16_hi v8, v184, s[62:63]
	global_store_short_d16_hi v8, v185, s[62:63] offset:128
	s_waitcnt vmcnt(36)
	v_pk_add_f32 v[26:27], v[136:137], v[138:139]
	v_fma_f32 v24, v12, v20, -v24
	v_fma_f32 v25, v12, v21, v25
	v_add_f32_e32 v20, v24, v26
	v_add_f32_e32 v21, v25, v27
	s_add_u32 s64, s62, s70
	s_addc_u32 s65, s63, s71
	v_bfe_u32 v186, v20, 16, 1
	v_bfe_u32 v187, v21, 16, 1
	v_mul_f32_e32 v24, v18, v21
	v_add3_u32 v186, v20, v186, s34
	v_add3_u32 v187, v21, v187, s34
	v_mul_f32_e32 v25, v18, v20
	global_store_short_d16_hi v8, v186, s[64:65]
	global_store_short_d16_hi v8, v187, s[64:65] offset:128
	s_waitcnt vmcnt(32)
	v_pk_add_f32 v[26:27], v[140:141], v[142:143]
	v_fma_f32 v24, v12, v20, -v24
	v_fma_f32 v25, v12, v21, v25
	v_add_f32_e32 v20, v24, v26
	v_add_f32_e32 v21, v25, v27
	s_add_u32 s66, s64, s70
	s_addc_u32 s67, s65, s71
	v_bfe_u32 v184, v20, 16, 1
	v_bfe_u32 v185, v21, 16, 1
	v_mul_f32_e32 v24, v18, v21
	v_add3_u32 v184, v20, v184, s34
	v_add3_u32 v185, v21, v185, s34
	v_mul_f32_e32 v25, v18, v20
	global_store_short_d16_hi v8, v184, s[66:67]
	global_store_short_d16_hi v8, v185, s[66:67] offset:128
	s_waitcnt vmcnt(28)
	v_pk_add_f32 v[26:27], v[144:145], v[146:147]
	v_fma_f32 v24, v12, v20, -v24
	v_fma_f32 v25, v12, v21, v25
	v_add_f32_e32 v20, v24, v26
	v_add_f32_e32 v21, v25, v27
	s_add_u32 s68, s66, s70
	s_addc_u32 s69, s67, s71
	v_bfe_u32 v186, v20, 16, 1
	v_bfe_u32 v187, v21, 16, 1
	v_mul_f32_e32 v24, v18, v21
	v_add3_u32 v186, v20, v186, s34
	v_add3_u32 v187, v21, v187, s34
	v_mul_f32_e32 v25, v18, v20
	global_store_short_d16_hi v8, v186, s[68:69]
	global_store_short_d16_hi v8, v187, s[68:69] offset:128
	s_waitcnt vmcnt(24)
	v_pk_add_f32 v[26:27], v[148:149], v[150:151]
	v_fma_f32 v24, v12, v20, -v24
	v_fma_f32 v25, v12, v21, v25
	v_add_f32_e32 v20, v24, v26
	v_add_f32_e32 v21, v25, v27
	s_add_i32 s26, s26, s96
	s_cmpk_gt_i32 s26, 0xff
	s_barrier
	s_cbranch_scc0 .LBB0_674
